# S5 item: Bbar stage's four B loads issued before the f64 table stage, stage unrolled with the same f64 operations
# baseline (speedup 1.0000x reference)
.Lssa_450:
	v_mov_b32_e32 v4, s2
	s_movk_i32 s4, 0xff
	s_waitcnt lgkmcnt(0)
	v_cmp_lt_i32_e32 vcc, s4, v4
	v_readfirstlane_b32 s83, v4
	s_mov_b64 s[4:5], -1
	s_cbranch_vccnz .Lssa_449
	s_ashr_i32 s82, s83, 2
	s_and_b32 s97, s83, 3
	s_lshl_b32 s98, s82, 12
	v_lshl_add_u32 v116, v208, 2, s98
	global_load_dword v117, v116, s[14:15]
	global_load_dword v118, v116, s[12:13] offset:2048
	global_load_dword v119, v116, s[14:15] offset:2048
	global_load_dword v116, v116, s[12:13]
	s_and_saveexec_b64 s[84:85], s[6:7]
	s_cbranch_execz .Lssa_466
	s_ashr_i32 s83, s82, 31
	s_lshl_b64 s[4:5], s[82:83], 2
	s_add_u32 s4, s36, s4
	s_addc_u32 s5, s37, s5
	global_load_dword v90, v9, s[4:5]
	v_lshl_or_b32 v48, s82, 6, v208
	v_ashrrev_i32_e32 v49, 31, v48
	v_lshlrev_b64 v[4:5], 2, v[48:49]
	v_lshl_add_u64 v[6:7], s[10:11], 0, v[4:5]
	global_load_dword v50, v[6:7], off
	v_lshl_add_u64 v[4:5], s[8:9], 0, v[4:5]
	global_load_dword v8, v[4:5], off
	v_mov_b32_e32 v37, v23
	v_mov_b64_e32 v[84:85], v[36:37]
	s_mov_b32 s4, 0x44800000
	s_mov_b32 s5, 0xc4866000
	v_mov_b64_e32 v[6:7], v[30:31]
	v_mov_b64_e32 v[58:59], v[40:41]
	v_mov_b64_e32 v[52:53], v[32:33]
	v_mov_b64_e32 v[60:61], v[42:43]
	v_mov_b32_e32 v44, v34
	v_mov_b64_e32 v[54:55], v[34:35]
	v_mov_b64_e32 v[86:87], v[44:45]
	v_mov_b64_e32 v[62:63], v[46:47]
	v_mov_b64_e32 v[56:57], v[38:39]
	v_mov_b32_e32 v82, v38
	v_mov_b32_e32 v83, v25
	s_waitcnt vmcnt(2)
	v_cvt_f64_f32_e32 v[4:5], v90
	v_mul_f64 v[88:89], v[4:5], s[58:59]
	v_rndne_f64_e32 v[88:89], v[88:89]
	v_fmac_f64_e32 v[4:5], s[60:61], v[88:89]
	v_fmac_f64_e32 v[4:5], s[62:63], v[88:89]
	v_cvt_i32_f64_e32 v37, v[88:89]
	v_fma_f64 v[88:89], s[64:65], v[4:5], v[12:13]
	v_fma_f64 v[88:89], v[4:5], v[88:89], v[14:15]
	v_fma_f64 v[88:89], v[4:5], v[88:89], v[16:17]
	v_fma_f64 v[88:89], v[4:5], v[88:89], v[18:19]
	v_fma_f64 v[88:89], v[4:5], v[88:89], v[20:21]
	v_fma_f64 v[88:89], v[4:5], v[88:89], v[22:23]
	v_fma_f64 v[88:89], v[4:5], v[88:89], v[24:25]
	v_fma_f64 v[88:89], v[4:5], v[88:89], v[26:27]
	v_fma_f64 v[88:89], v[4:5], v[88:89], v[28:29]
	v_fma_f64 v[88:89], v[4:5], v[88:89], 1.0
	v_fma_f64 v[4:5], v[4:5], v[88:89], 1.0
	v_ldexp_f64 v[4:5], v[4:5], v37
	v_cmp_nlt_f32_e32 vcc, s4, v90
	v_cmp_ngt_f32_e64 s[4:5], s5, v90
	s_waitcnt vmcnt(1)
	v_cvt_f64_f32_e32 v[50:51], v50
	v_cndmask_b32_e32 v5, v80, v5, vcc
	s_and_b64 vcc, s[4:5], vcc
	v_cndmask_b32_e64 v5, 0, v5, s[4:5]
	v_cndmask_b32_e32 v4, 0, v4, vcc
	v_mul_f64 v[88:89], v[4:5], v[50:51]
	v_mul_f64 v[90:91], v[88:89], s[66:67]
	v_rndne_f64_e32 v[90:91], v[90:91]
	v_fmac_f64_e32 v[88:89], s[68:69], v[90:91]
	v_fmac_f64_e32 v[88:89], s[70:71], v[90:91]
	v_cvt_i32_f64_e32 v37, v[90:91]
	v_mul_f64 v[90:91], v[88:89], v[88:89]
	v_fmac_f64_e32 v[6:7], s[72:73], v[90:91]
	v_fmac_f64_e32 v[58:59], s[74:75], v[90:91]
	v_fmac_f64_e32 v[52:53], v[90:91], v[6:7]
	v_fmac_f64_e32 v[60:61], v[90:91], v[58:59]
	v_fmac_f64_e32 v[54:55], v[90:91], v[52:53]
	v_fmac_f64_e32 v[86:87], v[90:91], v[60:61]
	v_fmac_f64_e32 v[84:85], v[90:91], v[54:55]
	v_fmac_f64_e32 v[62:63], v[90:91], v[86:87]
	v_fmac_f64_e32 v[56:57], v[90:91], v[84:85]
	v_fmac_f64_e32 v[82:83], v[90:91], v[62:63]
	v_and_b32_e32 v37, 3, v37
	v_fma_f64 v[6:7], v[90:91], v[56:57], 1.0
	v_fma_f64 v[52:53], v[90:91], v[82:83], -0.5
	v_mul_f64 v[6:7], v[88:89], v[6:7]
	v_fma_f64 v[52:53], v[90:91], v[52:53], 1.0
	v_cmp_lt_i32_e32 vcc, 0, v37
	s_and_saveexec_b64 s[4:5], vcc
	s_cbranch_execz .Lssa_462
	v_cmp_ne_u32_e32 vcc, 1, v37
	v_xor_b32_e32 v55, 0x80000000, v7
	v_mov_b32_e32 v54, v6
	s_and_saveexec_b64 s[86:87], vcc
	s_xor_b64 s[86:87], exec, s[86:87]
	v_cmp_eq_u32_e32 vcc, 2, v37
	v_xor_b32_e32 v37, 0x80000000, v53
	s_nop 0
	v_cndmask_b32_e32 v56, v52, v6, vcc
	v_cndmask_b32_e64 v57, -v53, -v7, vcc
	v_cndmask_b32_e32 v55, v7, v37, vcc
	v_cndmask_b32_e32 v54, v6, v52, vcc
	v_mov_b64_e32 v[6:7], v[56:57]
	s_andn2_saveexec_b64 s[86:87], s[86:87]
	v_mov_b64_e32 v[6:7], v[52:53]
	s_or_b64 exec, exec, s[86:87]
	v_mov_b64_e32 v[52:53], v[54:55]

.Lssa_467:
	v_and_b32_e32 v44, 64, v37
	v_bfe_i32 v84, v37, 6, 1
	v_cmp_eq_u32_e64 s[4:5], 0, v44
	v_and_b32_e32 v83, v84, v7
	v_and_b32_e32 v82, v84, v6
	v_cndmask_b32_e64 v85, v5, v81, s[4:5]
	v_and_b32_e32 v84, v84, v4
	v_and_b32_e32 v90, 0x80, v37
	v_add_u32_e32 v86, 0x200, v37
	v_cmp_lt_u32_e32 vcc, s94, v37
	v_mul_f64 v[88:89], v[50:51], v[84:85]
	v_and_b32_e32 v91, 0x100, v37
	v_and_b32_e32 v92, 0x200, v37
	v_and_b32_e32 v93, 0x400, v37
	s_or_b64 s[84:85], vcc, s[84:85]
	v_mov_b32_e32 v37, v86
	v_mul_f64 v[86:87], v[50:51], v[82:83]
	v_fmac_f64_e32 v[88:89], v[82:83], v[48:49]
	v_cmp_eq_u32_e32 vcc, 0, v90
	v_fma_f64 v[86:87], v[48:49], v[84:85], -v[86:87]
	s_nop 0
	v_cndmask_b32_e32 v83, v89, v83, vcc
	v_cndmask_b32_e32 v82, v88, v82, vcc
	v_cndmask_b32_e32 v85, v87, v85, vcc
	v_cndmask_b32_e32 v84, v86, v84, vcc
	v_mul_f64 v[88:89], v[52:53], v[82:83]
	v_mul_f64 v[86:87], v[54:55], v[82:83]
	v_fmac_f64_e32 v[88:89], v[54:55], v[84:85]
	v_cmp_eq_u32_e32 vcc, 0, v91
	v_fma_f64 v[86:87], v[52:53], v[84:85], -v[86:87]
	s_nop 0
	v_cndmask_b32_e32 v83, v89, v83, vcc
	v_cndmask_b32_e32 v82, v88, v82, vcc
	v_cndmask_b32_e32 v85, v87, v85, vcc
	v_cndmask_b32_e32 v84, v86, v84, vcc
	v_mul_f64 v[88:89], v[56:57], v[82:83]
	v_mul_f64 v[86:87], v[58:59], v[82:83]
	v_fmac_f64_e32 v[88:89], v[58:59], v[84:85]
	v_cmp_eq_u32_e32 vcc, 0, v92
	v_fma_f64 v[86:87], v[56:57], v[84:85], -v[86:87]
	s_nop 0
	v_cndmask_b32_e32 v83, v89, v83, vcc
	v_cndmask_b32_e32 v82, v88, v82, vcc
	v_cndmask_b32_e32 v85, v87, v85, vcc
	v_cndmask_b32_e32 v84, v86, v84, vcc
	v_mul_f64 v[86:87], v[62:63], v[82:83]
	v_mul_f64 v[88:89], v[60:61], v[82:83]
	v_fma_f64 v[86:87], v[60:61], v[84:85], -v[86:87]
	v_fmac_f64_e32 v[88:89], v[62:63], v[84:85]
	v_cmp_eq_u32_e32 vcc, 0, v93
	s_nop 1
	v_cndmask_b32_e32 v83, v89, v83, vcc
	v_cndmask_b32_e32 v82, v88, v82, vcc
	v_cndmask_b32_e32 v85, v87, v85, vcc
	v_cndmask_b32_e32 v84, v86, v84, vcc
	v_cvt_f32_f64_e32 v84, v[84:85]
	v_cvt_f32_f64_e32 v85, v[82:83]
	ds_write_b64 v8, v[84:85]
	v_add_u32_e32 v8, 0x1000, v8
	s_andn2_b64 exec, exec, s[84:85]
	s_cbranch_execnz .Lssa_467
	s_or_b64 exec, exec, s[84:85]
	v_and_b32_e32 v8, 0xfc, v74
	v_lshlrev_b32_e32 v8, 3, v8
	ds_read_b128 v[50:53], v8 offset:25104
	ds_read_b128 v[60:63], v8 offset:26128
	s_waitcnt vmcnt(0)
	s_waitcnt lgkmcnt(1)
	v_cvt_f64_f32_e32 v[56:57], v117
	v_cvt_f64_f32_e32 v[54:55], v116
	v_mul_f64 v[58:59], v[52:53], v[56:57]
	v_mul_f64 v[56:57], v[50:51], v[56:57]
	v_fma_f64 v[50:51], v[50:51], v[54:55], -v[58:59]
	v_fmac_f64_e32 v[56:57], v[52:53], v[54:55]
	v_cvt_f32_f64_e32 v50, v[50:51]
	v_cvt_f32_f64_e32 v51, v[56:57]
	ds_write_b64 v73, v[50:51]
	s_waitcnt lgkmcnt(1)
	v_cvt_f64_f32_e32 v[56:57], v119
	v_cvt_f64_f32_e32 v[54:55], v118
	v_mul_f64 v[58:59], v[62:63], v[56:57]
	v_mul_f64 v[56:57], v[60:61], v[56:57]
	v_fma_f64 v[60:61], v[60:61], v[54:55], -v[58:59]
	v_fmac_f64_e32 v[56:57], v[62:63], v[54:55]
	v_cvt_f32_f64_e32 v60, v[60:61]
	v_cvt_f32_f64_e32 v61, v[56:57]
	ds_write_b64 v73, v[60:61] offset:4096
	v_readfirstlane_b32 s98, v208
	s_lshr_b32 s98, s98, 6
	v_and_b32_e32 v12, 15, v210
	v_lshrrev_b32_e32 v13, 4, v210
	s_load_dwordx2 s[84:85], s[22:23], 0x80
	v_lshl_add_u32 v18, s82, 4, v12
	v_lshlrev_b32_e32 v18, 2, v18
	s_waitcnt lgkmcnt(0)
	global_load_dword v18, v18, s[84:85]
	v_lshrrev_b32_e32 v19, 1, v13
	v_lshl_add_u32 v14, v19, 4, v12
	v_lshlrev_b32_e32 v14, 3, v14
	v_and_b32_e32 v15, 1, v13
	v_lshl_add_u32 v14, v15, 2, v14
	v_cmp_eq_u32_e64 s[84:85], 1, v15
	s_lshl_b32 s4, s98, 10
	v_lshl_add_u32 v16, v19, 3, s4
	v_and_b32_e32 v15, 7, v12
	v_lshlrev_b32_e32 v15, 4, v15
	v_lshl_add_u32 v15, v12, 9, v15
	v_lshl_add_u32 v15, v19, 3, v15
	s_lshl_b32 s4, s98, 11
	v_lshl_add_u32 v17, v13, 8, s4
	v_lshl_add_u32 v17, v12, 2, v17
	v_mov_b32_e32 v20, 0
	v_mov_b32_e32 v21, 0
	v_mov_b32_e32 v22, 0
	v_mov_b32_e32 v23, 0
	v_mov_b32_e32 v24, 0
	v_mov_b32_e32 v25, 0
	v_mov_b32_e32 v26, 0
	v_mov_b32_e32 v27, 0
	s_waitcnt lgkmcnt(0)
	s_barrier
	ds_read_b64 v[30:31], v15 offset:16896
	ds_read_b64 v[32:33], v16 offset:0
	ds_read_b64 v[34:35], v16 offset:512
	ds_read_b32 v28, v14 offset:8704
	v_xor_b32_e32 v19, 0x10, v15
	ds_read_b64 v[52:53], v19 offset:16896
	ds_read_b64 v[54:55], v16 offset:16
	ds_read_b64 v[56:57], v16 offset:528
	ds_read_b32 v29, v14 offset:8960
	s_waitcnt lgkmcnt(4)
	v_pk_mul_f32 v[58:59], v[30:31], v[32:33] op_sel:[1,1] op_sel_hi:[0,1]
	v_pk_fma_f32 v[58:59], v[30:31], v[32:33], v[58:59] op_sel_hi:[1,0,1] neg_lo:[0,0,1]
	v_pk_mul_f32 v[60:61], v[30:31], v[34:35] op_sel:[1,1] op_sel_hi:[0,1]
	v_pk_fma_f32 v[60:61], v[30:31], v[34:35], v[60:61] op_sel_hi:[1,0,1] neg_lo:[0,0,1]
	v_cndmask_b32_e64 v62, v58, -v59, s[84:85]
	v_cndmask_b32_e64 v63, v60, -v61, s[84:85]
	s_nop 1
	v_mfma_f32_16x16x4_f32 v[20:23], v62, v28, v[20:23]
	v_mfma_f32_16x16x4_f32 v[24:27], v63, v28, v[24:27]
	v_xor_b32_e32 v19, 0x20, v15
	ds_read_b64 v[30:31], v19 offset:16896
	ds_read_b64 v[32:33], v16 offset:32
	ds_read_b64 v[34:35], v16 offset:544
	ds_read_b32 v28, v14 offset:9216
	s_waitcnt lgkmcnt(4)
	v_pk_mul_f32 v[58:59], v[52:53], v[54:55] op_sel:[1,1] op_sel_hi:[0,1]
	v_pk_fma_f32 v[58:59], v[52:53], v[54:55], v[58:59] op_sel_hi:[1,0,1] neg_lo:[0,0,1]
	v_pk_mul_f32 v[60:61], v[52:53], v[56:57] op_sel:[1,1] op_sel_hi:[0,1]
	v_pk_fma_f32 v[60:61], v[52:53], v[56:57], v[60:61] op_sel_hi:[1,0,1] neg_lo:[0,0,1]
	v_cndmask_b32_e64 v62, v58, -v59, s[84:85]
	v_cndmask_b32_e64 v63, v60, -v61, s[84:85]
	s_nop 1
	v_mfma_f32_16x16x4_f32 v[20:23], v62, v29, v[20:23]
	v_mfma_f32_16x16x4_f32 v[24:27], v63, v29, v[24:27]
	v_xor_b32_e32 v19, 0x30, v15
	ds_read_b64 v[52:53], v19 offset:16896
	ds_read_b64 v[54:55], v16 offset:48
	ds_read_b64 v[56:57], v16 offset:560
	ds_read_b32 v29, v14 offset:9472
	s_waitcnt lgkmcnt(4)
	v_pk_mul_f32 v[58:59], v[30:31], v[32:33] op_sel:[1,1] op_sel_hi:[0,1]
	v_pk_fma_f32 v[58:59], v[30:31], v[32:33], v[58:59] op_sel_hi:[1,0,1] neg_lo:[0,0,1]
	v_pk_mul_f32 v[60:61], v[30:31], v[34:35] op_sel:[1,1] op_sel_hi:[0,1]
	v_pk_fma_f32 v[60:61], v[30:31], v[34:35], v[60:61] op_sel_hi:[1,0,1] neg_lo:[0,0,1]
	v_cndmask_b32_e64 v62, v58, -v59, s[84:85]
	v_cndmask_b32_e64 v63, v60, -v61, s[84:85]
	s_nop 1
	v_mfma_f32_16x16x4_f32 v[20:23], v62, v28, v[20:23]
	v_mfma_f32_16x16x4_f32 v[24:27], v63, v28, v[24:27]
	v_xor_b32_e32 v19, 0x40, v15
	ds_read_b64 v[30:31], v19 offset:16896
	ds_read_b64 v[32:33], v16 offset:64
	ds_read_b64 v[34:35], v16 offset:576
	ds_read_b32 v28, v14 offset:9728
	s_waitcnt lgkmcnt(4)
	v_pk_mul_f32 v[58:59], v[52:53], v[54:55] op_sel:[1,1] op_sel_hi:[0,1]
	v_pk_fma_f32 v[58:59], v[52:53], v[54:55], v[58:59] op_sel_hi:[1,0,1] neg_lo:[0,0,1]
	v_pk_mul_f32 v[60:61], v[52:53], v[56:57] op_sel:[1,1] op_sel_hi:[0,1]
	v_pk_fma_f32 v[60:61], v[52:53], v[56:57], v[60:61] op_sel_hi:[1,0,1] neg_lo:[0,0,1]
	v_cndmask_b32_e64 v62, v58, -v59, s[84:85]
	v_cndmask_b32_e64 v63, v60, -v61, s[84:85]
	s_nop 1
	v_mfma_f32_16x16x4_f32 v[20:23], v62, v29, v[20:23]
	v_mfma_f32_16x16x4_f32 v[24:27], v63, v29, v[24:27]
	v_xor_b32_e32 v19, 0x50, v15
	ds_read_b64 v[52:53], v19 offset:16896
	ds_read_b64 v[54:55], v16 offset:80
	ds_read_b64 v[56:57], v16 offset:592
	ds_read_b32 v29, v14 offset:9984
	s_waitcnt lgkmcnt(4)
	v_pk_mul_f32 v[58:59], v[30:31], v[32:33] op_sel:[1,1] op_sel_hi:[0,1]
	v_pk_fma_f32 v[58:59], v[30:31], v[32:33], v[58:59] op_sel_hi:[1,0,1] neg_lo:[0,0,1]
	v_pk_mul_f32 v[60:61], v[30:31], v[34:35] op_sel:[1,1] op_sel_hi:[0,1]
	v_pk_fma_f32 v[60:61], v[30:31], v[34:35], v[60:61] op_sel_hi:[1,0,1] neg_lo:[0,0,1]
	v_cndmask_b32_e64 v62, v58, -v59, s[84:85]
	v_cndmask_b32_e64 v63, v60, -v61, s[84:85]
	s_nop 1
	v_mfma_f32_16x16x4_f32 v[20:23], v62, v28, v[20:23]
	v_mfma_f32_16x16x4_f32 v[24:27], v63, v28, v[24:27]
	v_xor_b32_e32 v19, 0x60, v15
	ds_read_b64 v[30:31], v19 offset:16896
	ds_read_b64 v[32:33], v16 offset:96
	ds_read_b64 v[34:35], v16 offset:608
	ds_read_b32 v28, v14 offset:10240
	s_waitcnt lgkmcnt(4)
	v_pk_mul_f32 v[58:59], v[52:53], v[54:55] op_sel:[1,1] op_sel_hi:[0,1]
	v_pk_fma_f32 v[58:59], v[52:53], v[54:55], v[58:59] op_sel_hi:[1,0,1] neg_lo:[0,0,1]
	v_pk_mul_f32 v[60:61], v[52:53], v[56:57] op_sel:[1,1] op_sel_hi:[0,1]
	v_pk_fma_f32 v[60:61], v[52:53], v[56:57], v[60:61] op_sel_hi:[1,0,1] neg_lo:[0,0,1]
	v_cndmask_b32_e64 v62, v58, -v59, s[84:85]
	v_cndmask_b32_e64 v63, v60, -v61, s[84:85]
	s_nop 1
	v_mfma_f32_16x16x4_f32 v[20:23], v62, v29, v[20:23]
	v_mfma_f32_16x16x4_f32 v[24:27], v63, v29, v[24:27]
	v_xor_b32_e32 v19, 0x70, v15
	ds_read_b64 v[52:53], v19 offset:16896
	ds_read_b64 v[54:55], v16 offset:112
	ds_read_b64 v[56:57], v16 offset:624
	ds_read_b32 v29, v14 offset:10496
	s_waitcnt lgkmcnt(4)
	v_pk_mul_f32 v[58:59], v[30:31], v[32:33] op_sel:[1,1] op_sel_hi:[0,1]
	v_pk_fma_f32 v[58:59], v[30:31], v[32:33], v[58:59] op_sel_hi:[1,0,1] neg_lo:[0,0,1]
	v_pk_mul_f32 v[60:61], v[30:31], v[34:35] op_sel:[1,1] op_sel_hi:[0,1]
	v_pk_fma_f32 v[60:61], v[30:31], v[34:35], v[60:61] op_sel_hi:[1,0,1] neg_lo:[0,0,1]
	v_cndmask_b32_e64 v62, v58, -v59, s[84:85]
	v_cndmask_b32_e64 v63, v60, -v61, s[84:85]
	s_nop 1
	v_mfma_f32_16x16x4_f32 v[20:23], v62, v28, v[20:23]
	v_mfma_f32_16x16x4_f32 v[24:27], v63, v28, v[24:27]
	v_xor_b32_e32 v19, 0x80, v15
	ds_read_b64 v[30:31], v19 offset:16896
	ds_read_b64 v[32:33], v16 offset:128
	ds_read_b64 v[34:35], v16 offset:640
	ds_read_b32 v28, v14 offset:10752
	s_waitcnt lgkmcnt(4)
	v_pk_mul_f32 v[58:59], v[52:53], v[54:55] op_sel:[1,1] op_sel_hi:[0,1]
	v_pk_fma_f32 v[58:59], v[52:53], v[54:55], v[58:59] op_sel_hi:[1,0,1] neg_lo:[0,0,1]
	v_pk_mul_f32 v[60:61], v[52:53], v[56:57] op_sel:[1,1] op_sel_hi:[0,1]
	v_pk_fma_f32 v[60:61], v[52:53], v[56:57], v[60:61] op_sel_hi:[1,0,1] neg_lo:[0,0,1]
	v_cndmask_b32_e64 v62, v58, -v59, s[84:85]
	v_cndmask_b32_e64 v63, v60, -v61, s[84:85]
	s_nop 1
	v_mfma_f32_16x16x4_f32 v[20:23], v62, v29, v[20:23]
	v_mfma_f32_16x16x4_f32 v[24:27], v63, v29, v[24:27]
	v_xor_b32_e32 v19, 0x90, v15
	ds_read_b64 v[52:53], v19 offset:16896
	ds_read_b64 v[54:55], v16 offset:144
	ds_read_b64 v[56:57], v16 offset:656
	ds_read_b32 v29, v14 offset:11008
	s_waitcnt lgkmcnt(4)
	v_pk_mul_f32 v[58:59], v[30:31], v[32:33] op_sel:[1,1] op_sel_hi:[0,1]
	v_pk_fma_f32 v[58:59], v[30:31], v[32:33], v[58:59] op_sel_hi:[1,0,1] neg_lo:[0,0,1]
	v_pk_mul_f32 v[60:61], v[30:31], v[34:35] op_sel:[1,1] op_sel_hi:[0,1]
	v_pk_fma_f32 v[60:61], v[30:31], v[34:35], v[60:61] op_sel_hi:[1,0,1] neg_lo:[0,0,1]
	v_cndmask_b32_e64 v62, v58, -v59, s[84:85]
	v_cndmask_b32_e64 v63, v60, -v61, s[84:85]
	s_nop 1
	v_mfma_f32_16x16x4_f32 v[20:23], v62, v28, v[20:23]
	v_mfma_f32_16x16x4_f32 v[24:27], v63, v28, v[24:27]
	v_xor_b32_e32 v19, 0xa0, v15
	ds_read_b64 v[30:31], v19 offset:16896
	ds_read_b64 v[32:33], v16 offset:160
	ds_read_b64 v[34:35], v16 offset:672
	ds_read_b32 v28, v14 offset:11264
	s_waitcnt lgkmcnt(4)
	v_pk_mul_f32 v[58:59], v[52:53], v[54:55] op_sel:[1,1] op_sel_hi:[0,1]
	v_pk_fma_f32 v[58:59], v[52:53], v[54:55], v[58:59] op_sel_hi:[1,0,1] neg_lo:[0,0,1]
	v_pk_mul_f32 v[60:61], v[52:53], v[56:57] op_sel:[1,1] op_sel_hi:[0,1]
	v_pk_fma_f32 v[60:61], v[52:53], v[56:57], v[60:61] op_sel_hi:[1,0,1] neg_lo:[0,0,1]
	v_cndmask_b32_e64 v62, v58, -v59, s[84:85]
	v_cndmask_b32_e64 v63, v60, -v61, s[84:85]
	s_nop 1
	v_mfma_f32_16x16x4_f32 v[20:23], v62, v29, v[20:23]
	v_mfma_f32_16x16x4_f32 v[24:27], v63, v29, v[24:27]
	v_xor_b32_e32 v19, 0xb0, v15
	ds_read_b64 v[52:53], v19 offset:16896
	ds_read_b64 v[54:55], v16 offset:176
	ds_read_b64 v[56:57], v16 offset:688
	ds_read_b32 v29, v14 offset:11520
	s_waitcnt lgkmcnt(4)
	v_pk_mul_f32 v[58:59], v[30:31], v[32:33] op_sel:[1,1] op_sel_hi:[0,1]
	v_pk_fma_f32 v[58:59], v[30:31], v[32:33], v[58:59] op_sel_hi:[1,0,1] neg_lo:[0,0,1]
	v_pk_mul_f32 v[60:61], v[30:31], v[34:35] op_sel:[1,1] op_sel_hi:[0,1]
	v_pk_fma_f32 v[60:61], v[30:31], v[34:35], v[60:61] op_sel_hi:[1,0,1] neg_lo:[0,0,1]
	v_cndmask_b32_e64 v62, v58, -v59, s[84:85]
	v_cndmask_b32_e64 v63, v60, -v61, s[84:85]
	s_nop 1
	v_mfma_f32_16x16x4_f32 v[20:23], v62, v28, v[20:23]
	v_mfma_f32_16x16x4_f32 v[24:27], v63, v28, v[24:27]
	v_xor_b32_e32 v19, 0xc0, v15
	ds_read_b64 v[30:31], v19 offset:16896
	ds_read_b64 v[32:33], v16 offset:192
	ds_read_b64 v[34:35], v16 offset:704
	ds_read_b32 v28, v14 offset:11776
	s_waitcnt lgkmcnt(4)
	v_pk_mul_f32 v[58:59], v[52:53], v[54:55] op_sel:[1,1] op_sel_hi:[0,1]
	v_pk_fma_f32 v[58:59], v[52:53], v[54:55], v[58:59] op_sel_hi:[1,0,1] neg_lo:[0,0,1]
	v_pk_mul_f32 v[60:61], v[52:53], v[56:57] op_sel:[1,1] op_sel_hi:[0,1]
	v_pk_fma_f32 v[60:61], v[52:53], v[56:57], v[60:61] op_sel_hi:[1,0,1] neg_lo:[0,0,1]
	v_cndmask_b32_e64 v62, v58, -v59, s[84:85]
	v_cndmask_b32_e64 v63, v60, -v61, s[84:85]
	s_nop 1
	v_mfma_f32_16x16x4_f32 v[20:23], v62, v29, v[20:23]
	v_mfma_f32_16x16x4_f32 v[24:27], v63, v29, v[24:27]
	v_xor_b32_e32 v19, 0xd0, v15
	ds_read_b64 v[52:53], v19 offset:16896
	ds_read_b64 v[54:55], v16 offset:208
	ds_read_b64 v[56:57], v16 offset:720
	ds_read_b32 v29, v14 offset:12032
	s_waitcnt lgkmcnt(4)
	v_pk_mul_f32 v[58:59], v[30:31], v[32:33] op_sel:[1,1] op_sel_hi:[0,1]
	v_pk_fma_f32 v[58:59], v[30:31], v[32:33], v[58:59] op_sel_hi:[1,0,1] neg_lo:[0,0,1]
	v_pk_mul_f32 v[60:61], v[30:31], v[34:35] op_sel:[1,1] op_sel_hi:[0,1]
	v_pk_fma_f32 v[60:61], v[30:31], v[34:35], v[60:61] op_sel_hi:[1,0,1] neg_lo:[0,0,1]
	v_cndmask_b32_e64 v62, v58, -v59, s[84:85]
	v_cndmask_b32_e64 v63, v60, -v61, s[84:85]
	s_nop 1
	v_mfma_f32_16x16x4_f32 v[20:23], v62, v28, v[20:23]
	v_mfma_f32_16x16x4_f32 v[24:27], v63, v28, v[24:27]
	v_xor_b32_e32 v19, 0xe0, v15
	ds_read_b64 v[30:31], v19 offset:16896
	ds_read_b64 v[32:33], v16 offset:224
	ds_read_b64 v[34:35], v16 offset:736
	ds_read_b32 v28, v14 offset:12288
	s_waitcnt lgkmcnt(4)
	v_pk_mul_f32 v[58:59], v[52:53], v[54:55] op_sel:[1,1] op_sel_hi:[0,1]
	v_pk_fma_f32 v[58:59], v[52:53], v[54:55], v[58:59] op_sel_hi:[1,0,1] neg_lo:[0,0,1]
	v_pk_mul_f32 v[60:61], v[52:53], v[56:57] op_sel:[1,1] op_sel_hi:[0,1]
	v_pk_fma_f32 v[60:61], v[52:53], v[56:57], v[60:61] op_sel_hi:[1,0,1] neg_lo:[0,0,1]
	v_cndmask_b32_e64 v62, v58, -v59, s[84:85]
	v_cndmask_b32_e64 v63, v60, -v61, s[84:85]
	s_nop 1
	v_mfma_f32_16x16x4_f32 v[20:23], v62, v29, v[20:23]
	v_mfma_f32_16x16x4_f32 v[24:27], v63, v29, v[24:27]
	v_xor_b32_e32 v19, 0xf0, v15
	ds_read_b64 v[52:53], v19 offset:16896
	ds_read_b64 v[54:55], v16 offset:240
	ds_read_b64 v[56:57], v16 offset:752
	ds_read_b32 v29, v14 offset:12544
	s_waitcnt lgkmcnt(4)
	v_pk_mul_f32 v[58:59], v[30:31], v[32:33] op_sel:[1,1] op_sel_hi:[0,1]
	v_pk_fma_f32 v[58:59], v[30:31], v[32:33], v[58:59] op_sel_hi:[1,0,1] neg_lo:[0,0,1]
	v_pk_mul_f32 v[60:61], v[30:31], v[34:35] op_sel:[1,1] op_sel_hi:[0,1]
	v_pk_fma_f32 v[60:61], v[30:31], v[34:35], v[60:61] op_sel_hi:[1,0,1] neg_lo:[0,0,1]
	v_cndmask_b32_e64 v62, v58, -v59, s[84:85]
	v_cndmask_b32_e64 v63, v60, -v61, s[84:85]
	s_nop 1
	v_mfma_f32_16x16x4_f32 v[20:23], v62, v28, v[20:23]
	v_mfma_f32_16x16x4_f32 v[24:27], v63, v28, v[24:27]
	v_xor_b32_e32 v19, 0x100, v15
	ds_read_b64 v[30:31], v19 offset:16896
	ds_read_b64 v[32:33], v16 offset:256
	ds_read_b64 v[34:35], v16 offset:768
	ds_read_b32 v28, v14 offset:12800
	s_waitcnt lgkmcnt(4)
	v_pk_mul_f32 v[58:59], v[52:53], v[54:55] op_sel:[1,1] op_sel_hi:[0,1]
	v_pk_fma_f32 v[58:59], v[52:53], v[54:55], v[58:59] op_sel_hi:[1,0,1] neg_lo:[0,0,1]
	v_pk_mul_f32 v[60:61], v[52:53], v[56:57] op_sel:[1,1] op_sel_hi:[0,1]
	v_pk_fma_f32 v[60:61], v[52:53], v[56:57], v[60:61] op_sel_hi:[1,0,1] neg_lo:[0,0,1]
	v_cndmask_b32_e64 v62, v58, -v59, s[84:85]
	v_cndmask_b32_e64 v63, v60, -v61, s[84:85]
	s_nop 1
	v_mfma_f32_16x16x4_f32 v[20:23], v62, v29, v[20:23]
	v_mfma_f32_16x16x4_f32 v[24:27], v63, v29, v[24:27]
	v_xor_b32_e32 v19, 0x110, v15
	ds_read_b64 v[52:53], v19 offset:16896
	ds_read_b64 v[54:55], v16 offset:272
	ds_read_b64 v[56:57], v16 offset:784
	ds_read_b32 v29, v14 offset:13056
	s_waitcnt lgkmcnt(4)
	v_pk_mul_f32 v[58:59], v[30:31], v[32:33] op_sel:[1,1] op_sel_hi:[0,1]
	v_pk_fma_f32 v[58:59], v[30:31], v[32:33], v[58:59] op_sel_hi:[1,0,1] neg_lo:[0,0,1]
	v_pk_mul_f32 v[60:61], v[30:31], v[34:35] op_sel:[1,1] op_sel_hi:[0,1]
	v_pk_fma_f32 v[60:61], v[30:31], v[34:35], v[60:61] op_sel_hi:[1,0,1] neg_lo:[0,0,1]
	v_cndmask_b32_e64 v62, v58, -v59, s[84:85]
	v_cndmask_b32_e64 v63, v60, -v61, s[84:85]
	s_nop 1
	v_mfma_f32_16x16x4_f32 v[20:23], v62, v28, v[20:23]
	v_mfma_f32_16x16x4_f32 v[24:27], v63, v28, v[24:27]
	v_xor_b32_e32 v19, 0x120, v15
	ds_read_b64 v[30:31], v19 offset:16896
	ds_read_b64 v[32:33], v16 offset:288
	ds_read_b64 v[34:35], v16 offset:800
	ds_read_b32 v28, v14 offset:13312
	s_waitcnt lgkmcnt(4)
	v_pk_mul_f32 v[58:59], v[52:53], v[54:55] op_sel:[1,1] op_sel_hi:[0,1]
	v_pk_fma_f32 v[58:59], v[52:53], v[54:55], v[58:59] op_sel_hi:[1,0,1] neg_lo:[0,0,1]
	v_pk_mul_f32 v[60:61], v[52:53], v[56:57] op_sel:[1,1] op_sel_hi:[0,1]
	v_pk_fma_f32 v[60:61], v[52:53], v[56:57], v[60:61] op_sel_hi:[1,0,1] neg_lo:[0,0,1]
	v_cndmask_b32_e64 v62, v58, -v59, s[84:85]
	v_cndmask_b32_e64 v63, v60, -v61, s[84:85]
	s_nop 1
	v_mfma_f32_16x16x4_f32 v[20:23], v62, v29, v[20:23]
	v_mfma_f32_16x16x4_f32 v[24:27], v63, v29, v[24:27]
	v_xor_b32_e32 v19, 0x130, v15
	ds_read_b64 v[52:53], v19 offset:16896
	ds_read_b64 v[54:55], v16 offset:304
	ds_read_b64 v[56:57], v16 offset:816
	ds_read_b32 v29, v14 offset:13568
	s_waitcnt lgkmcnt(4)
	v_pk_mul_f32 v[58:59], v[30:31], v[32:33] op_sel:[1,1] op_sel_hi:[0,1]
	v_pk_fma_f32 v[58:59], v[30:31], v[32:33], v[58:59] op_sel_hi:[1,0,1] neg_lo:[0,0,1]
	v_pk_mul_f32 v[60:61], v[30:31], v[34:35] op_sel:[1,1] op_sel_hi:[0,1]
	v_pk_fma_f32 v[60:61], v[30:31], v[34:35], v[60:61] op_sel_hi:[1,0,1] neg_lo:[0,0,1]
	v_cndmask_b32_e64 v62, v58, -v59, s[84:85]
	v_cndmask_b32_e64 v63, v60, -v61, s[84:85]
	s_nop 1
	v_mfma_f32_16x16x4_f32 v[20:23], v62, v28, v[20:23]
	v_mfma_f32_16x16x4_f32 v[24:27], v63, v28, v[24:27]
	v_xor_b32_e32 v19, 0x140, v15
	ds_read_b64 v[30:31], v19 offset:16896
	ds_read_b64 v[32:33], v16 offset:320
	ds_read_b64 v[34:35], v16 offset:832
	ds_read_b32 v28, v14 offset:13824
	s_waitcnt lgkmcnt(4)
	v_pk_mul_f32 v[58:59], v[52:53], v[54:55] op_sel:[1,1] op_sel_hi:[0,1]
	v_pk_fma_f32 v[58:59], v[52:53], v[54:55], v[58:59] op_sel_hi:[1,0,1] neg_lo:[0,0,1]
	v_pk_mul_f32 v[60:61], v[52:53], v[56:57] op_sel:[1,1] op_sel_hi:[0,1]
	v_pk_fma_f32 v[60:61], v[52:53], v[56:57], v[60:61] op_sel_hi:[1,0,1] neg_lo:[0,0,1]
	v_cndmask_b32_e64 v62, v58, -v59, s[84:85]
	v_cndmask_b32_e64 v63, v60, -v61, s[84:85]
	s_nop 1
	v_mfma_f32_16x16x4_f32 v[20:23], v62, v29, v[20:23]
	v_mfma_f32_16x16x4_f32 v[24:27], v63, v29, v[24:27]
	v_xor_b32_e32 v19, 0x150, v15
	ds_read_b64 v[52:53], v19 offset:16896
	ds_read_b64 v[54:55], v16 offset:336
	ds_read_b64 v[56:57], v16 offset:848
	ds_read_b32 v29, v14 offset:14080
	s_waitcnt lgkmcnt(4)
	v_pk_mul_f32 v[58:59], v[30:31], v[32:33] op_sel:[1,1] op_sel_hi:[0,1]
	v_pk_fma_f32 v[58:59], v[30:31], v[32:33], v[58:59] op_sel_hi:[1,0,1] neg_lo:[0,0,1]
	v_pk_mul_f32 v[60:61], v[30:31], v[34:35] op_sel:[1,1] op_sel_hi:[0,1]
	v_pk_fma_f32 v[60:61], v[30:31], v[34:35], v[60:61] op_sel_hi:[1,0,1] neg_lo:[0,0,1]
	v_cndmask_b32_e64 v62, v58, -v59, s[84:85]
	v_cndmask_b32_e64 v63, v60, -v61, s[84:85]
	s_nop 1
	v_mfma_f32_16x16x4_f32 v[20:23], v62, v28, v[20:23]
	v_mfma_f32_16x16x4_f32 v[24:27], v63, v28, v[24:27]
	v_xor_b32_e32 v19, 0x160, v15
	ds_read_b64 v[30:31], v19 offset:16896
	ds_read_b64 v[32:33], v16 offset:352
	ds_read_b64 v[34:35], v16 offset:864
	ds_read_b32 v28, v14 offset:14336
	s_waitcnt lgkmcnt(4)
	v_pk_mul_f32 v[58:59], v[52:53], v[54:55] op_sel:[1,1] op_sel_hi:[0,1]
	v_pk_fma_f32 v[58:59], v[52:53], v[54:55], v[58:59] op_sel_hi:[1,0,1] neg_lo:[0,0,1]
	v_pk_mul_f32 v[60:61], v[52:53], v[56:57] op_sel:[1,1] op_sel_hi:[0,1]
	v_pk_fma_f32 v[60:61], v[52:53], v[56:57], v[60:61] op_sel_hi:[1,0,1] neg_lo:[0,0,1]
	v_cndmask_b32_e64 v62, v58, -v59, s[84:85]
	v_cndmask_b32_e64 v63, v60, -v61, s[84:85]
	s_nop 1
	v_mfma_f32_16x16x4_f32 v[20:23], v62, v29, v[20:23]
	v_mfma_f32_16x16x4_f32 v[24:27], v63, v29, v[24:27]
	v_xor_b32_e32 v19, 0x170, v15
	ds_read_b64 v[52:53], v19 offset:16896
	ds_read_b64 v[54:55], v16 offset:368
	ds_read_b64 v[56:57], v16 offset:880
	ds_read_b32 v29, v14 offset:14592
	s_waitcnt lgkmcnt(4)
	v_pk_mul_f32 v[58:59], v[30:31], v[32:33] op_sel:[1,1] op_sel_hi:[0,1]
	v_pk_fma_f32 v[58:59], v[30:31], v[32:33], v[58:59] op_sel_hi:[1,0,1] neg_lo:[0,0,1]
	v_pk_mul_f32 v[60:61], v[30:31], v[34:35] op_sel:[1,1] op_sel_hi:[0,1]
	v_pk_fma_f32 v[60:61], v[30:31], v[34:35], v[60:61] op_sel_hi:[1,0,1] neg_lo:[0,0,1]
	v_cndmask_b32_e64 v62, v58, -v59, s[84:85]
	v_cndmask_b32_e64 v63, v60, -v61, s[84:85]
	s_nop 1
	v_mfma_f32_16x16x4_f32 v[20:23], v62, v28, v[20:23]
	v_mfma_f32_16x16x4_f32 v[24:27], v63, v28, v[24:27]
	v_xor_b32_e32 v19, 0x180, v15
	ds_read_b64 v[30:31], v19 offset:16896
	ds_read_b64 v[32:33], v16 offset:384
	ds_read_b64 v[34:35], v16 offset:896
	ds_read_b32 v28, v14 offset:14848
	s_waitcnt lgkmcnt(4)
	v_pk_mul_f32 v[58:59], v[52:53], v[54:55] op_sel:[1,1] op_sel_hi:[0,1]
	v_pk_fma_f32 v[58:59], v[52:53], v[54:55], v[58:59] op_sel_hi:[1,0,1] neg_lo:[0,0,1]
	v_pk_mul_f32 v[60:61], v[52:53], v[56:57] op_sel:[1,1] op_sel_hi:[0,1]
	v_pk_fma_f32 v[60:61], v[52:53], v[56:57], v[60:61] op_sel_hi:[1,0,1] neg_lo:[0,0,1]
	v_cndmask_b32_e64 v62, v58, -v59, s[84:85]
	v_cndmask_b32_e64 v63, v60, -v61, s[84:85]
	s_nop 1
	v_mfma_f32_16x16x4_f32 v[20:23], v62, v29, v[20:23]
	v_mfma_f32_16x16x4_f32 v[24:27], v63, v29, v[24:27]
	v_xor_b32_e32 v19, 0x190, v15
	ds_read_b64 v[52:53], v19 offset:16896
	ds_read_b64 v[54:55], v16 offset:400
	ds_read_b64 v[56:57], v16 offset:912
	ds_read_b32 v29, v14 offset:15104
	s_waitcnt lgkmcnt(4)
	v_pk_mul_f32 v[58:59], v[30:31], v[32:33] op_sel:[1,1] op_sel_hi:[0,1]
	v_pk_fma_f32 v[58:59], v[30:31], v[32:33], v[58:59] op_sel_hi:[1,0,1] neg_lo:[0,0,1]
	v_pk_mul_f32 v[60:61], v[30:31], v[34:35] op_sel:[1,1] op_sel_hi:[0,1]
	v_pk_fma_f32 v[60:61], v[30:31], v[34:35], v[60:61] op_sel_hi:[1,0,1] neg_lo:[0,0,1]
	v_cndmask_b32_e64 v62, v58, -v59, s[84:85]
	v_cndmask_b32_e64 v63, v60, -v61, s[84:85]
	s_nop 1
	v_mfma_f32_16x16x4_f32 v[20:23], v62, v28, v[20:23]
	v_mfma_f32_16x16x4_f32 v[24:27], v63, v28, v[24:27]
	v_xor_b32_e32 v19, 0x1a0, v15
	ds_read_b64 v[30:31], v19 offset:16896
	ds_read_b64 v[32:33], v16 offset:416
	ds_read_b64 v[34:35], v16 offset:928
	ds_read_b32 v28, v14 offset:15360
	s_waitcnt lgkmcnt(4)
	v_pk_mul_f32 v[58:59], v[52:53], v[54:55] op_sel:[1,1] op_sel_hi:[0,1]
	v_pk_fma_f32 v[58:59], v[52:53], v[54:55], v[58:59] op_sel_hi:[1,0,1] neg_lo:[0,0,1]
	v_pk_mul_f32 v[60:61], v[52:53], v[56:57] op_sel:[1,1] op_sel_hi:[0,1]
	v_pk_fma_f32 v[60:61], v[52:53], v[56:57], v[60:61] op_sel_hi:[1,0,1] neg_lo:[0,0,1]
	v_cndmask_b32_e64 v62, v58, -v59, s[84:85]
	v_cndmask_b32_e64 v63, v60, -v61, s[84:85]
	s_nop 1
	v_mfma_f32_16x16x4_f32 v[20:23], v62, v29, v[20:23]
	v_mfma_f32_16x16x4_f32 v[24:27], v63, v29, v[24:27]
	v_xor_b32_e32 v19, 0x1b0, v15
	ds_read_b64 v[52:53], v19 offset:16896
	ds_read_b64 v[54:55], v16 offset:432
	ds_read_b64 v[56:57], v16 offset:944
	ds_read_b32 v29, v14 offset:15616
	s_waitcnt lgkmcnt(4)
	v_pk_mul_f32 v[58:59], v[30:31], v[32:33] op_sel:[1,1] op_sel_hi:[0,1]
	v_pk_fma_f32 v[58:59], v[30:31], v[32:33], v[58:59] op_sel_hi:[1,0,1] neg_lo:[0,0,1]
	v_pk_mul_f32 v[60:61], v[30:31], v[34:35] op_sel:[1,1] op_sel_hi:[0,1]
	v_pk_fma_f32 v[60:61], v[30:31], v[34:35], v[60:61] op_sel_hi:[1,0,1] neg_lo:[0,0,1]
	v_cndmask_b32_e64 v62, v58, -v59, s[84:85]
	v_cndmask_b32_e64 v63, v60, -v61, s[84:85]
	s_nop 1
	v_mfma_f32_16x16x4_f32 v[20:23], v62, v28, v[20:23]
	v_mfma_f32_16x16x4_f32 v[24:27], v63, v28, v[24:27]
	v_xor_b32_e32 v19, 0x1c0, v15
	ds_read_b64 v[30:31], v19 offset:16896
	ds_read_b64 v[32:33], v16 offset:448
	ds_read_b64 v[34:35], v16 offset:960
	ds_read_b32 v28, v14 offset:15872
	s_waitcnt lgkmcnt(4)
	v_pk_mul_f32 v[58:59], v[52:53], v[54:55] op_sel:[1,1] op_sel_hi:[0,1]
	v_pk_fma_f32 v[58:59], v[52:53], v[54:55], v[58:59] op_sel_hi:[1,0,1] neg_lo:[0,0,1]
	v_pk_mul_f32 v[60:61], v[52:53], v[56:57] op_sel:[1,1] op_sel_hi:[0,1]
	v_pk_fma_f32 v[60:61], v[52:53], v[56:57], v[60:61] op_sel_hi:[1,0,1] neg_lo:[0,0,1]
	v_cndmask_b32_e64 v62, v58, -v59, s[84:85]
	v_cndmask_b32_e64 v63, v60, -v61, s[84:85]
	s_nop 1
	v_mfma_f32_16x16x4_f32 v[20:23], v62, v29, v[20:23]
	v_mfma_f32_16x16x4_f32 v[24:27], v63, v29, v[24:27]
	v_xor_b32_e32 v19, 0x1d0, v15
	ds_read_b64 v[52:53], v19 offset:16896
	ds_read_b64 v[54:55], v16 offset:464
	ds_read_b64 v[56:57], v16 offset:976
	ds_read_b32 v29, v14 offset:16128
	s_waitcnt lgkmcnt(4)
	v_pk_mul_f32 v[58:59], v[30:31], v[32:33] op_sel:[1,1] op_sel_hi:[0,1]
	v_pk_fma_f32 v[58:59], v[30:31], v[32:33], v[58:59] op_sel_hi:[1,0,1] neg_lo:[0,0,1]
	v_pk_mul_f32 v[60:61], v[30:31], v[34:35] op_sel:[1,1] op_sel_hi:[0,1]
	v_pk_fma_f32 v[60:61], v[30:31], v[34:35], v[60:61] op_sel_hi:[1,0,1] neg_lo:[0,0,1]
	v_cndmask_b32_e64 v62, v58, -v59, s[84:85]
	v_cndmask_b32_e64 v63, v60, -v61, s[84:85]
	s_nop 1
	v_mfma_f32_16x16x4_f32 v[20:23], v62, v28, v[20:23]
	v_mfma_f32_16x16x4_f32 v[24:27], v63, v28, v[24:27]
	v_xor_b32_e32 v19, 0x1e0, v15
	ds_read_b64 v[30:31], v19 offset:16896
	ds_read_b64 v[32:33], v16 offset:480
	ds_read_b64 v[34:35], v16 offset:992
	ds_read_b32 v28, v14 offset:16384
	s_waitcnt lgkmcnt(4)
	v_pk_mul_f32 v[58:59], v[52:53], v[54:55] op_sel:[1,1] op_sel_hi:[0,1]
	v_pk_fma_f32 v[58:59], v[52:53], v[54:55], v[58:59] op_sel_hi:[1,0,1] neg_lo:[0,0,1]
	v_pk_mul_f32 v[60:61], v[52:53], v[56:57] op_sel:[1,1] op_sel_hi:[0,1]
	v_pk_fma_f32 v[60:61], v[52:53], v[56:57], v[60:61] op_sel_hi:[1,0,1] neg_lo:[0,0,1]
	v_cndmask_b32_e64 v62, v58, -v59, s[84:85]
	v_cndmask_b32_e64 v63, v60, -v61, s[84:85]
	s_nop 1
	v_mfma_f32_16x16x4_f32 v[20:23], v62, v29, v[20:23]
	v_mfma_f32_16x16x4_f32 v[24:27], v63, v29, v[24:27]
	v_xor_b32_e32 v19, 0x1f0, v15
	ds_read_b64 v[52:53], v19 offset:16896
	ds_read_b64 v[54:55], v16 offset:496
	ds_read_b64 v[56:57], v16 offset:1008
	ds_read_b32 v29, v14 offset:16640
	s_waitcnt lgkmcnt(4)
	v_pk_mul_f32 v[58:59], v[30:31], v[32:33] op_sel:[1,1] op_sel_hi:[0,1]
	v_pk_fma_f32 v[58:59], v[30:31], v[32:33], v[58:59] op_sel_hi:[1,0,1] neg_lo:[0,0,1]
	v_pk_mul_f32 v[60:61], v[30:31], v[34:35] op_sel:[1,1] op_sel_hi:[0,1]
	v_pk_fma_f32 v[60:61], v[30:31], v[34:35], v[60:61] op_sel_hi:[1,0,1] neg_lo:[0,0,1]
	v_cndmask_b32_e64 v62, v58, -v59, s[84:85]
	v_cndmask_b32_e64 v63, v60, -v61, s[84:85]
	s_nop 1
	v_mfma_f32_16x16x4_f32 v[20:23], v62, v28, v[20:23]
	v_mfma_f32_16x16x4_f32 v[24:27], v63, v28, v[24:27]
	s_waitcnt lgkmcnt(0)
	v_pk_mul_f32 v[58:59], v[52:53], v[54:55] op_sel:[1,1] op_sel_hi:[0,1]
	v_pk_fma_f32 v[58:59], v[52:53], v[54:55], v[58:59] op_sel_hi:[1,0,1] neg_lo:[0,0,1]
	v_pk_mul_f32 v[60:61], v[52:53], v[56:57] op_sel:[1,1] op_sel_hi:[0,1]
	v_pk_fma_f32 v[60:61], v[52:53], v[56:57], v[60:61] op_sel_hi:[1,0,1] neg_lo:[0,0,1]
	v_cndmask_b32_e64 v62, v58, -v59, s[84:85]
	v_cndmask_b32_e64 v63, v60, -v61, s[84:85]
	s_nop 1
	v_mfma_f32_16x16x4_f32 v[20:23], v62, v29, v[20:23]
	v_mfma_f32_16x16x4_f32 v[24:27], v63, v29, v[24:27]
	s_cmp_eq_u32 s98, 0
	s_cselect_b64 s[4:5], -1, 0
	s_waitcnt vmcnt(0)
	s_nop 10
	v_lshl_add_u32 v19, v13, 2, 0
	v_cmp_eq_u32_e32 vcc, v19, v12
	s_nop 3
	s_and_b64 vcc, vcc, s[4:5]
	s_nop 3
	v_cndmask_b32_e32 v19, 0, v18, vcc
	v_add_f32_e32 v20, v20, v19
	v_lshl_add_u32 v19, v13, 2, 1
	v_cmp_eq_u32_e32 vcc, v19, v12
	s_nop 3
	s_and_b64 vcc, vcc, s[4:5]
	s_nop 3
	v_cndmask_b32_e32 v19, 0, v18, vcc
	v_add_f32_e32 v21, v21, v19
	v_lshl_add_u32 v19, v13, 2, 2
	v_cmp_eq_u32_e32 vcc, v19, v12
	s_nop 3
	s_and_b64 vcc, vcc, s[4:5]
	s_nop 3
	v_cndmask_b32_e32 v19, 0, v18, vcc
	v_add_f32_e32 v22, v22, v19
	v_lshl_add_u32 v19, v13, 2, 3
	v_cmp_eq_u32_e32 vcc, v19, v12
	s_nop 3
	s_and_b64 vcc, vcc, s[4:5]
	s_nop 3
	v_cndmask_b32_e32 v19, 0, v18, vcc
	v_add_f32_e32 v23, v23, v19
	s_lshl_b32 s86, s97, 6
	s_lshl_b32 s87, s82, 8
	s_mov_b32 s91, 0
	ds_write_b32 v17, v20 offset:25088
	ds_write_b32 v17, v21 offset:25152
	ds_write_b32 v17, v22 offset:25216
	ds_write_b32 v17, v23 offset:25280
	ds_write_b32 v17, v24 offset:26112
	ds_write_b32 v17, v25 offset:26176
	ds_write_b32 v17, v26 offset:26240
	ds_write_b32 v17, v27 offset:26304
	s_waitcnt lgkmcnt(0)
	s_barrier
	s_branch .Lssa_493
